# norm row loops: next row's loads no longer wait for the previous row's stores (different rows never alias)
# speedup vs baseline: 1.0019x; 1.0019x over previous
.LBB0_151:
	s_andn2_b64 vcc, exec, s[14:15]
	s_cbranch_vccnz .LBB0_153
	s_lshl_b64 s[14:15], s[12:13], 12
	s_add_u32 s14, s18, s14
	s_addc_u32 s15, s7, s15
	s_nop 0
	v_lshlrev_b32_e32 v14, 1, v130
	global_load_dwordx4 v[2:5], v14, s[14:15] nt
	global_load_dwordx4 v[6:9], v14, s[14:15] offset:1024 nt
	global_load_dwordx4 v[10:13], v14, s[14:15] offset:2048 nt
	global_load_dwordx4 v[34:37], v14, s[14:15] offset:3072 nt
	s_waitcnt vmcnt(3)
	v_lshlrev_b32_e32 v30, 16, v2
	v_and_b32_e32 v31, 0xffff0000, v2
	v_lshlrev_b32_e32 v32, 16, v3
	v_and_b32_e32 v33, 0xffff0000, v3
	v_lshlrev_b32_e32 v26, 16, v4
	v_and_b32_e32 v27, 0xffff0000, v4
	v_lshlrev_b32_e32 v28, 16, v5
	v_and_b32_e32 v29, 0xffff0000, v5
	s_waitcnt vmcnt(2)
	v_lshlrev_b32_e32 v22, 16, v6
	v_and_b32_e32 v23, 0xffff0000, v6
	v_lshlrev_b32_e32 v24, 16, v7
	v_and_b32_e32 v25, 0xffff0000, v7
	v_lshlrev_b32_e32 v18, 16, v8
	v_and_b32_e32 v19, 0xffff0000, v8
	v_lshlrev_b32_e32 v20, 16, v9
	v_and_b32_e32 v21, 0xffff0000, v9
	s_waitcnt vmcnt(1)
	v_lshlrev_b32_e32 v14, 16, v10
	v_and_b32_e32 v15, 0xffff0000, v10
	v_lshlrev_b32_e32 v16, 16, v11
	v_and_b32_e32 v17, 0xffff0000, v11
	v_lshlrev_b32_e32 v10, 16, v12
	v_and_b32_e32 v11, 0xffff0000, v12
	v_lshlrev_b32_e32 v12, 16, v13
	v_and_b32_e32 v13, 0xffff0000, v13
	s_waitcnt vmcnt(0)
	v_lshlrev_b32_e32 v6, 16, v34
	v_and_b32_e32 v7, 0xffff0000, v34
	v_lshlrev_b32_e32 v8, 16, v35
	v_and_b32_e32 v9, 0xffff0000, v35
	v_lshlrev_b32_e32 v2, 16, v36
	v_and_b32_e32 v3, 0xffff0000, v36
	v_lshlrev_b32_e32 v4, 16, v37
	v_and_b32_e32 v5, 0xffff0000, v37

.LBB0_1032:
	s_andn2_b64 vcc, exec, s[12:13]
	s_cbranch_vccnz .LBB0_1034
	s_and_b64 s[12:13], s[4:5], exec
	s_cselect_b32 s3, s7, s1
	s_cselect_b32 s18, s6, s0
	s_lshl_b64 s[12:13], s[8:9], 12
	s_add_u32 s12, s18, s12
	s_addc_u32 s13, s3, s13
	s_nop 0
	v_lshlrev_b32_e32 v14, 1, v130
	global_load_dwordx4 v[2:5], v14, s[12:13] nt
	global_load_dwordx4 v[6:9], v14, s[12:13] offset:1024 nt
	global_load_dwordx4 v[10:13], v14, s[12:13] offset:2048 nt
	global_load_dwordx4 v[34:37], v14, s[12:13] offset:3072 nt
	s_waitcnt vmcnt(3)
	v_lshlrev_b32_e32 v30, 16, v2
	v_and_b32_e32 v31, 0xffff0000, v2
	v_lshlrev_b32_e32 v32, 16, v3
	v_and_b32_e32 v33, 0xffff0000, v3
	v_lshlrev_b32_e32 v26, 16, v4
	v_and_b32_e32 v27, 0xffff0000, v4
	v_lshlrev_b32_e32 v28, 16, v5
	v_and_b32_e32 v29, 0xffff0000, v5
	s_waitcnt vmcnt(2)
	v_lshlrev_b32_e32 v22, 16, v6
	v_and_b32_e32 v23, 0xffff0000, v6
	v_lshlrev_b32_e32 v24, 16, v7
	v_and_b32_e32 v25, 0xffff0000, v7
	v_lshlrev_b32_e32 v18, 16, v8
	v_and_b32_e32 v19, 0xffff0000, v8
	v_lshlrev_b32_e32 v20, 16, v9
	v_and_b32_e32 v21, 0xffff0000, v9
	s_waitcnt vmcnt(1)
	v_lshlrev_b32_e32 v14, 16, v10
	v_and_b32_e32 v15, 0xffff0000, v10
	v_lshlrev_b32_e32 v16, 16, v11
	v_and_b32_e32 v17, 0xffff0000, v11
	v_lshlrev_b32_e32 v10, 16, v12
	v_and_b32_e32 v11, 0xffff0000, v12
	v_lshlrev_b32_e32 v12, 16, v13
	v_and_b32_e32 v13, 0xffff0000, v13
	s_waitcnt vmcnt(0)
	v_lshlrev_b32_e32 v6, 16, v34
	v_and_b32_e32 v7, 0xffff0000, v34
	v_lshlrev_b32_e32 v8, 16, v35
	v_and_b32_e32 v9, 0xffff0000, v35
	v_lshlrev_b32_e32 v2, 16, v36
	v_and_b32_e32 v3, 0xffff0000, v36
	v_lshlrev_b32_e32 v4, 16, v37
	v_and_b32_e32 v5, 0xffff0000, v37
